# phase-2 triangular inversion rewritten with packed f32 FMAs (same operation order, fewer instructions on wave 0)
# speedup vs baseline: 1.0231x; 1.0197x over previous
.LBB0_664:
	s_or_saveexec_b64 s[12:13], s[16:17]
	v_and_b32_e32 v95, 31, v94
	s_xor_b64 exec, exec, s[12:13]
	s_cbranch_execz .LBB0_666
	v_and_b32_e32 v0, 32, v94
	v_lshlrev_b32_e32 v1, 8, v0
	v_lshlrev_b32_e32 v2, 2, v0
	v_add3_u32 v11, s91, v1, v2
	v_mov_b32_e32 v241, 0
	v_mov_b32_e32 v249, 0
	ds_read_b128 v[204:207], v11 offset:256
	v_cmp_eq_u32_e32 vcc, 0, v95
	v_lshl_add_u32 v244, v95, 1, s95
	v_mad_u32_u24 v0, v0, s93, v244
	v_cndmask_b32_e64 v12, 0, 1.0, vcc
	v_cmp_eq_u32_e32 vcc, 1, v95
	s_nop 1
	v_cndmask_b32_e64 v248, 0, 1.0, vcc
	v_cmp_eq_u32_e32 vcc, 2, v95
	ds_read_b128 v[172:175], v11 offset:512
	s_waitcnt lgkmcnt(1)
	v_cndmask_b32_e64 v240, 0, 1.0, vcc
	v_fma_f32 v13, -v204, v12, v248
	v_cmp_eq_u32_e32 vcc, 3, v95
	ds_read_b128 v[204:207], v11 offset:768
	s_waitcnt lgkmcnt(1)
	v_pk_fma_f32 v[242:243], v[172:173], v[12:13], v[240:241] neg_lo:[1,0,0] neg_hi:[1,0,0]
	v_cndmask_b32_e64 v248, 0, 1.0, vcc
	v_add_f32_e32 v14, v242, v243
	v_cmp_eq_u32_e32 vcc, 4, v95
	ds_read_b128 v[172:175], v11 offset:1024
	s_waitcnt lgkmcnt(1)
	v_pk_fma_f32 v[242:243], v[204:205], v[12:13], v[248:249] neg_lo:[1,0,0] neg_hi:[1,0,0]
	v_cndmask_b32_e64 v240, 0, 1.0, vcc
	v_fma_f32 v242, -v206, v14, v242
	v_add_f32_e32 v15, v242, v243
	v_cmp_eq_u32_e32 vcc, 5, v95
	ds_read_b128 v[204:207], v11 offset:1280
	ds_read_b128 v[208:211], v11 offset:1296
	s_waitcnt lgkmcnt(2)
	v_pk_fma_f32 v[242:243], v[172:173], v[12:13], v[240:241] neg_lo:[1,0,0] neg_hi:[1,0,0]
	v_pk_fma_f32 v[242:243], v[174:175], v[14:15], v[242:243] neg_lo:[1,0,0] neg_hi:[1,0,0]
	v_cndmask_b32_e64 v248, 0, 1.0, vcc
	v_add_f32_e32 v16, v242, v243
	v_cmp_eq_u32_e32 vcc, 6, v95
	ds_read_b128 v[172:175], v11 offset:1536
	ds_read_b128 v[176:179], v11 offset:1552
	s_waitcnt lgkmcnt(2)
	v_pk_fma_f32 v[242:243], v[204:205], v[12:13], v[248:249] neg_lo:[1,0,0] neg_hi:[1,0,0]
	v_pk_fma_f32 v[242:243], v[206:207], v[14:15], v[242:243] neg_lo:[1,0,0] neg_hi:[1,0,0]
	v_cndmask_b32_e64 v240, 0, 1.0, vcc
	v_fma_f32 v242, -v208, v16, v242
	v_add_f32_e32 v17, v242, v243
	v_cmp_eq_u32_e32 vcc, 7, v95
	ds_read_b128 v[204:207], v11 offset:1792
	ds_read_b128 v[208:211], v11 offset:1808
	s_waitcnt lgkmcnt(2)
	v_pk_fma_f32 v[242:243], v[172:173], v[12:13], v[240:241] neg_lo:[1,0,0] neg_hi:[1,0,0]
	v_pk_fma_f32 v[242:243], v[174:175], v[14:15], v[242:243] neg_lo:[1,0,0] neg_hi:[1,0,0]
	v_pk_fma_f32 v[242:243], v[176:177], v[16:17], v[242:243] neg_lo:[1,0,0] neg_hi:[1,0,0]
	v_cndmask_b32_e64 v248, 0, 1.0, vcc
	v_add_f32_e32 v18, v242, v243
	v_cmp_eq_u32_e32 vcc, 8, v95
	ds_read_b128 v[172:175], v11 offset:2048
	ds_read_b128 v[176:179], v11 offset:2064
	s_waitcnt lgkmcnt(2)
	v_pk_fma_f32 v[242:243], v[204:205], v[12:13], v[248:249] neg_lo:[1,0,0] neg_hi:[1,0,0]
	v_pk_fma_f32 v[242:243], v[206:207], v[14:15], v[242:243] neg_lo:[1,0,0] neg_hi:[1,0,0]
	v_pk_fma_f32 v[242:243], v[208:209], v[16:17], v[242:243] neg_lo:[1,0,0] neg_hi:[1,0,0]
	v_cndmask_b32_e64 v240, 0, 1.0, vcc
	v_fma_f32 v242, -v210, v18, v242
	v_add_f32_e32 v19, v242, v243
	v_cmp_eq_u32_e32 vcc, 9, v95
	ds_read_b128 v[204:207], v11 offset:2304
	ds_read_b128 v[208:211], v11 offset:2320
	ds_read_b128 v[212:215], v11 offset:2336
	s_waitcnt lgkmcnt(3)
	v_pk_fma_f32 v[242:243], v[172:173], v[12:13], v[240:241] neg_lo:[1,0,0] neg_hi:[1,0,0]
	v_pk_fma_f32 v[242:243], v[174:175], v[14:15], v[242:243] neg_lo:[1,0,0] neg_hi:[1,0,0]
	v_pk_fma_f32 v[242:243], v[176:177], v[16:17], v[242:243] neg_lo:[1,0,0] neg_hi:[1,0,0]
	v_pk_fma_f32 v[242:243], v[178:179], v[18:19], v[242:243] neg_lo:[1,0,0] neg_hi:[1,0,0]
	v_cndmask_b32_e64 v248, 0, 1.0, vcc
	v_add_f32_e32 v20, v242, v243
	v_cmp_eq_u32_e32 vcc, 10, v95
	ds_read_b128 v[172:175], v11 offset:2560
	ds_read_b128 v[176:179], v11 offset:2576
	ds_read_b128 v[180:183], v11 offset:2592
	s_waitcnt lgkmcnt(3)
	v_pk_fma_f32 v[242:243], v[204:205], v[12:13], v[248:249] neg_lo:[1,0,0] neg_hi:[1,0,0]
	v_pk_fma_f32 v[242:243], v[206:207], v[14:15], v[242:243] neg_lo:[1,0,0] neg_hi:[1,0,0]
	v_pk_fma_f32 v[242:243], v[208:209], v[16:17], v[242:243] neg_lo:[1,0,0] neg_hi:[1,0,0]
	v_pk_fma_f32 v[242:243], v[210:211], v[18:19], v[242:243] neg_lo:[1,0,0] neg_hi:[1,0,0]
	v_cndmask_b32_e64 v240, 0, 1.0, vcc
	v_fma_f32 v242, -v212, v20, v242
	v_add_f32_e32 v21, v242, v243
	v_cmp_eq_u32_e32 vcc, 11, v95
	ds_read_b128 v[204:207], v11 offset:2816
	ds_read_b128 v[208:211], v11 offset:2832
	ds_read_b128 v[212:215], v11 offset:2848
	s_waitcnt lgkmcnt(3)
	v_pk_fma_f32 v[242:243], v[172:173], v[12:13], v[240:241] neg_lo:[1,0,0] neg_hi:[1,0,0]
	v_pk_fma_f32 v[242:243], v[174:175], v[14:15], v[242:243] neg_lo:[1,0,0] neg_hi:[1,0,0]
	v_pk_fma_f32 v[242:243], v[176:177], v[16:17], v[242:243] neg_lo:[1,0,0] neg_hi:[1,0,0]
	v_pk_fma_f32 v[242:243], v[178:179], v[18:19], v[242:243] neg_lo:[1,0,0] neg_hi:[1,0,0]
	v_pk_fma_f32 v[242:243], v[180:181], v[20:21], v[242:243] neg_lo:[1,0,0] neg_hi:[1,0,0]
	v_cndmask_b32_e64 v248, 0, 1.0, vcc
	v_add_f32_e32 v22, v242, v243
	v_cmp_eq_u32_e32 vcc, 12, v95
	ds_read_b128 v[172:175], v11 offset:3072
	ds_read_b128 v[176:179], v11 offset:3088
	ds_read_b128 v[180:183], v11 offset:3104
	s_waitcnt lgkmcnt(3)
	v_pk_fma_f32 v[242:243], v[204:205], v[12:13], v[248:249] neg_lo:[1,0,0] neg_hi:[1,0,0]
	v_pk_fma_f32 v[242:243], v[206:207], v[14:15], v[242:243] neg_lo:[1,0,0] neg_hi:[1,0,0]
	v_pk_fma_f32 v[242:243], v[208:209], v[16:17], v[242:243] neg_lo:[1,0,0] neg_hi:[1,0,0]
	v_pk_fma_f32 v[242:243], v[210:211], v[18:19], v[242:243] neg_lo:[1,0,0] neg_hi:[1,0,0]
	v_pk_fma_f32 v[242:243], v[212:213], v[20:21], v[242:243] neg_lo:[1,0,0] neg_hi:[1,0,0]
	v_cndmask_b32_e64 v240, 0, 1.0, vcc
	v_fma_f32 v242, -v214, v22, v242
	v_add_f32_e32 v23, v242, v243
	v_cmp_eq_u32_e32 vcc, 13, v95
	ds_read_b128 v[204:207], v11 offset:3328
	ds_read_b128 v[208:211], v11 offset:3344
	ds_read_b128 v[212:215], v11 offset:3360
	ds_read_b128 v[216:219], v11 offset:3376
	s_waitcnt lgkmcnt(4)
	v_pk_fma_f32 v[242:243], v[172:173], v[12:13], v[240:241] neg_lo:[1,0,0] neg_hi:[1,0,0]
	v_pk_fma_f32 v[242:243], v[174:175], v[14:15], v[242:243] neg_lo:[1,0,0] neg_hi:[1,0,0]
	v_pk_fma_f32 v[242:243], v[176:177], v[16:17], v[242:243] neg_lo:[1,0,0] neg_hi:[1,0,0]
	v_pk_fma_f32 v[242:243], v[178:179], v[18:19], v[242:243] neg_lo:[1,0,0] neg_hi:[1,0,0]
	v_pk_fma_f32 v[242:243], v[180:181], v[20:21], v[242:243] neg_lo:[1,0,0] neg_hi:[1,0,0]
	v_pk_fma_f32 v[242:243], v[182:183], v[22:23], v[242:243] neg_lo:[1,0,0] neg_hi:[1,0,0]
	v_cndmask_b32_e64 v248, 0, 1.0, vcc
	v_add_f32_e32 v24, v242, v243
	v_cmp_eq_u32_e32 vcc, 14, v95
	ds_read_b128 v[172:175], v11 offset:3584
	ds_read_b128 v[176:179], v11 offset:3600
	ds_read_b128 v[180:183], v11 offset:3616
	ds_read_b128 v[184:187], v11 offset:3632
	s_waitcnt lgkmcnt(4)
	v_pk_fma_f32 v[242:243], v[204:205], v[12:13], v[248:249] neg_lo:[1,0,0] neg_hi:[1,0,0]
	v_pk_fma_f32 v[242:243], v[206:207], v[14:15], v[242:243] neg_lo:[1,0,0] neg_hi:[1,0,0]
	v_pk_fma_f32 v[242:243], v[208:209], v[16:17], v[242:243] neg_lo:[1,0,0] neg_hi:[1,0,0]
	v_pk_fma_f32 v[242:243], v[210:211], v[18:19], v[242:243] neg_lo:[1,0,0] neg_hi:[1,0,0]
	v_pk_fma_f32 v[242:243], v[212:213], v[20:21], v[242:243] neg_lo:[1,0,0] neg_hi:[1,0,0]
	v_pk_fma_f32 v[242:243], v[214:215], v[22:23], v[242:243] neg_lo:[1,0,0] neg_hi:[1,0,0]
	v_cndmask_b32_e64 v240, 0, 1.0, vcc
	v_fma_f32 v242, -v216, v24, v242
	v_add_f32_e32 v25, v242, v243
	v_cmp_eq_u32_e32 vcc, 15, v95
	ds_read_b128 v[204:207], v11 offset:3840
	ds_read_b128 v[208:211], v11 offset:3856
	ds_read_b128 v[212:215], v11 offset:3872
	ds_read_b128 v[216:219], v11 offset:3888
	s_waitcnt lgkmcnt(4)
	v_pk_fma_f32 v[242:243], v[172:173], v[12:13], v[240:241] neg_lo:[1,0,0] neg_hi:[1,0,0]
	v_pk_fma_f32 v[242:243], v[174:175], v[14:15], v[242:243] neg_lo:[1,0,0] neg_hi:[1,0,0]
	v_pk_fma_f32 v[242:243], v[176:177], v[16:17], v[242:243] neg_lo:[1,0,0] neg_hi:[1,0,0]
	v_pk_fma_f32 v[242:243], v[178:179], v[18:19], v[242:243] neg_lo:[1,0,0] neg_hi:[1,0,0]
	v_pk_fma_f32 v[242:243], v[180:181], v[20:21], v[242:243] neg_lo:[1,0,0] neg_hi:[1,0,0]
	v_pk_fma_f32 v[242:243], v[182:183], v[22:23], v[242:243] neg_lo:[1,0,0] neg_hi:[1,0,0]
	v_pk_fma_f32 v[242:243], v[184:185], v[24:25], v[242:243] neg_lo:[1,0,0] neg_hi:[1,0,0]
	v_cndmask_b32_e64 v248, 0, 1.0, vcc
	v_add_f32_e32 v26, v242, v243
	v_cmp_eq_u32_e32 vcc, 16, v95
	ds_read_b128 v[172:175], v11 offset:4096
	ds_read_b128 v[176:179], v11 offset:4112
	ds_read_b128 v[180:183], v11 offset:4128
	ds_read_b128 v[184:187], v11 offset:4144
	s_waitcnt lgkmcnt(4)
	v_pk_fma_f32 v[242:243], v[204:205], v[12:13], v[248:249] neg_lo:[1,0,0] neg_hi:[1,0,0]
	v_pk_fma_f32 v[242:243], v[206:207], v[14:15], v[242:243] neg_lo:[1,0,0] neg_hi:[1,0,0]
	v_pk_fma_f32 v[242:243], v[208:209], v[16:17], v[242:243] neg_lo:[1,0,0] neg_hi:[1,0,0]
	v_pk_fma_f32 v[242:243], v[210:211], v[18:19], v[242:243] neg_lo:[1,0,0] neg_hi:[1,0,0]
	v_pk_fma_f32 v[242:243], v[212:213], v[20:21], v[242:243] neg_lo:[1,0,0] neg_hi:[1,0,0]
	v_pk_fma_f32 v[242:243], v[214:215], v[22:23], v[242:243] neg_lo:[1,0,0] neg_hi:[1,0,0]
	v_pk_fma_f32 v[242:243], v[216:217], v[24:25], v[242:243] neg_lo:[1,0,0] neg_hi:[1,0,0]
	v_cndmask_b32_e64 v240, 0, 1.0, vcc
	v_fma_f32 v242, -v218, v26, v242
	v_add_f32_e32 v27, v242, v243
	v_cmp_eq_u32_e32 vcc, 17, v95
	ds_read_b128 v[204:207], v11 offset:4352
	ds_read_b128 v[208:211], v11 offset:4368
	ds_read_b128 v[212:215], v11 offset:4384
	ds_read_b128 v[216:219], v11 offset:4400
	ds_read_b128 v[220:223], v11 offset:4416
	s_waitcnt lgkmcnt(5)
	v_pk_fma_f32 v[242:243], v[172:173], v[12:13], v[240:241] neg_lo:[1,0,0] neg_hi:[1,0,0]
	v_pk_fma_f32 v[242:243], v[174:175], v[14:15], v[242:243] neg_lo:[1,0,0] neg_hi:[1,0,0]
	v_pk_fma_f32 v[242:243], v[176:177], v[16:17], v[242:243] neg_lo:[1,0,0] neg_hi:[1,0,0]
	v_pk_fma_f32 v[242:243], v[178:179], v[18:19], v[242:243] neg_lo:[1,0,0] neg_hi:[1,0,0]
	v_pk_fma_f32 v[242:243], v[180:181], v[20:21], v[242:243] neg_lo:[1,0,0] neg_hi:[1,0,0]
	v_pk_fma_f32 v[242:243], v[182:183], v[22:23], v[242:243] neg_lo:[1,0,0] neg_hi:[1,0,0]
	v_pk_fma_f32 v[242:243], v[184:185], v[24:25], v[242:243] neg_lo:[1,0,0] neg_hi:[1,0,0]
	v_pk_fma_f32 v[242:243], v[186:187], v[26:27], v[242:243] neg_lo:[1,0,0] neg_hi:[1,0,0]
	v_cndmask_b32_e64 v248, 0, 1.0, vcc
	v_add_f32_e32 v28, v242, v243
	v_cmp_eq_u32_e32 vcc, 18, v95
	ds_read_b128 v[172:175], v11 offset:4608
	ds_read_b128 v[176:179], v11 offset:4624
	ds_read_b128 v[180:183], v11 offset:4640
	ds_read_b128 v[184:187], v11 offset:4656
	ds_read_b128 v[188:191], v11 offset:4672
	s_waitcnt lgkmcnt(5)
	v_pk_fma_f32 v[242:243], v[204:205], v[12:13], v[248:249] neg_lo:[1,0,0] neg_hi:[1,0,0]
	v_pk_fma_f32 v[242:243], v[206:207], v[14:15], v[242:243] neg_lo:[1,0,0] neg_hi:[1,0,0]
	v_pk_fma_f32 v[242:243], v[208:209], v[16:17], v[242:243] neg_lo:[1,0,0] neg_hi:[1,0,0]
	v_pk_fma_f32 v[242:243], v[210:211], v[18:19], v[242:243] neg_lo:[1,0,0] neg_hi:[1,0,0]
	v_pk_fma_f32 v[242:243], v[212:213], v[20:21], v[242:243] neg_lo:[1,0,0] neg_hi:[1,0,0]
	v_pk_fma_f32 v[242:243], v[214:215], v[22:23], v[242:243] neg_lo:[1,0,0] neg_hi:[1,0,0]
	v_pk_fma_f32 v[242:243], v[216:217], v[24:25], v[242:243] neg_lo:[1,0,0] neg_hi:[1,0,0]
	v_pk_fma_f32 v[242:243], v[218:219], v[26:27], v[242:243] neg_lo:[1,0,0] neg_hi:[1,0,0]
	v_cndmask_b32_e64 v240, 0, 1.0, vcc
	v_fma_f32 v242, -v220, v28, v242
	v_add_f32_e32 v29, v242, v243
	v_cmp_eq_u32_e32 vcc, 19, v95
	ds_read_b128 v[204:207], v11 offset:4864
	ds_read_b128 v[208:211], v11 offset:4880
	ds_read_b128 v[212:215], v11 offset:4896
	ds_read_b128 v[216:219], v11 offset:4912
	ds_read_b128 v[220:223], v11 offset:4928
	s_waitcnt lgkmcnt(5)
	v_pk_fma_f32 v[242:243], v[172:173], v[12:13], v[240:241] neg_lo:[1,0,0] neg_hi:[1,0,0]
	v_pk_fma_f32 v[242:243], v[174:175], v[14:15], v[242:243] neg_lo:[1,0,0] neg_hi:[1,0,0]
	v_pk_fma_f32 v[242:243], v[176:177], v[16:17], v[242:243] neg_lo:[1,0,0] neg_hi:[1,0,0]
	v_pk_fma_f32 v[242:243], v[178:179], v[18:19], v[242:243] neg_lo:[1,0,0] neg_hi:[1,0,0]
	v_pk_fma_f32 v[242:243], v[180:181], v[20:21], v[242:243] neg_lo:[1,0,0] neg_hi:[1,0,0]
	v_pk_fma_f32 v[242:243], v[182:183], v[22:23], v[242:243] neg_lo:[1,0,0] neg_hi:[1,0,0]
	v_pk_fma_f32 v[242:243], v[184:185], v[24:25], v[242:243] neg_lo:[1,0,0] neg_hi:[1,0,0]
	v_pk_fma_f32 v[242:243], v[186:187], v[26:27], v[242:243] neg_lo:[1,0,0] neg_hi:[1,0,0]
	v_pk_fma_f32 v[242:243], v[188:189], v[28:29], v[242:243] neg_lo:[1,0,0] neg_hi:[1,0,0]
	v_cndmask_b32_e64 v248, 0, 1.0, vcc
	v_add_f32_e32 v30, v242, v243
	v_cmp_eq_u32_e32 vcc, 20, v95
	ds_read_b128 v[172:175], v11 offset:5120
	ds_read_b128 v[176:179], v11 offset:5136
	ds_read_b128 v[180:183], v11 offset:5152
	ds_read_b128 v[184:187], v11 offset:5168
	ds_read_b128 v[188:191], v11 offset:5184
	s_waitcnt lgkmcnt(5)
	v_pk_fma_f32 v[242:243], v[204:205], v[12:13], v[248:249] neg_lo:[1,0,0] neg_hi:[1,0,0]
	v_pk_fma_f32 v[242:243], v[206:207], v[14:15], v[242:243] neg_lo:[1,0,0] neg_hi:[1,0,0]
	v_pk_fma_f32 v[242:243], v[208:209], v[16:17], v[242:243] neg_lo:[1,0,0] neg_hi:[1,0,0]
	v_pk_fma_f32 v[242:243], v[210:211], v[18:19], v[242:243] neg_lo:[1,0,0] neg_hi:[1,0,0]
	v_pk_fma_f32 v[242:243], v[212:213], v[20:21], v[242:243] neg_lo:[1,0,0] neg_hi:[1,0,0]
	v_pk_fma_f32 v[242:243], v[214:215], v[22:23], v[242:243] neg_lo:[1,0,0] neg_hi:[1,0,0]
	v_pk_fma_f32 v[242:243], v[216:217], v[24:25], v[242:243] neg_lo:[1,0,0] neg_hi:[1,0,0]
	v_pk_fma_f32 v[242:243], v[218:219], v[26:27], v[242:243] neg_lo:[1,0,0] neg_hi:[1,0,0]
	v_pk_fma_f32 v[242:243], v[220:221], v[28:29], v[242:243] neg_lo:[1,0,0] neg_hi:[1,0,0]
	v_cndmask_b32_e64 v240, 0, 1.0, vcc
	v_fma_f32 v242, -v222, v30, v242
	v_add_f32_e32 v31, v242, v243
	v_cmp_eq_u32_e32 vcc, 21, v95
	ds_read_b128 v[204:207], v11 offset:5376
	ds_read_b128 v[208:211], v11 offset:5392
	ds_read_b128 v[212:215], v11 offset:5408
	ds_read_b128 v[216:219], v11 offset:5424
	ds_read_b128 v[220:223], v11 offset:5440
	ds_read_b128 v[224:227], v11 offset:5456
	s_waitcnt lgkmcnt(6)
	v_pk_fma_f32 v[242:243], v[172:173], v[12:13], v[240:241] neg_lo:[1,0,0] neg_hi:[1,0,0]
	v_pk_fma_f32 v[242:243], v[174:175], v[14:15], v[242:243] neg_lo:[1,0,0] neg_hi:[1,0,0]
	v_pk_fma_f32 v[242:243], v[176:177], v[16:17], v[242:243] neg_lo:[1,0,0] neg_hi:[1,0,0]
	v_pk_fma_f32 v[242:243], v[178:179], v[18:19], v[242:243] neg_lo:[1,0,0] neg_hi:[1,0,0]
	v_pk_fma_f32 v[242:243], v[180:181], v[20:21], v[242:243] neg_lo:[1,0,0] neg_hi:[1,0,0]
	v_pk_fma_f32 v[242:243], v[182:183], v[22:23], v[242:243] neg_lo:[1,0,0] neg_hi:[1,0,0]
	v_pk_fma_f32 v[242:243], v[184:185], v[24:25], v[242:243] neg_lo:[1,0,0] neg_hi:[1,0,0]
	v_pk_fma_f32 v[242:243], v[186:187], v[26:27], v[242:243] neg_lo:[1,0,0] neg_hi:[1,0,0]
	v_pk_fma_f32 v[242:243], v[188:189], v[28:29], v[242:243] neg_lo:[1,0,0] neg_hi:[1,0,0]
	v_pk_fma_f32 v[242:243], v[190:191], v[30:31], v[242:243] neg_lo:[1,0,0] neg_hi:[1,0,0]
	v_cndmask_b32_e64 v248, 0, 1.0, vcc
	v_add_f32_e32 v32, v242, v243
	v_cmp_eq_u32_e32 vcc, 22, v95
	ds_read_b128 v[172:175], v11 offset:5632
	ds_read_b128 v[176:179], v11 offset:5648
	ds_read_b128 v[180:183], v11 offset:5664
	ds_read_b128 v[184:187], v11 offset:5680
	ds_read_b128 v[188:191], v11 offset:5696
	ds_read_b128 v[192:195], v11 offset:5712
	s_waitcnt lgkmcnt(6)
	v_pk_fma_f32 v[242:243], v[204:205], v[12:13], v[248:249] neg_lo:[1,0,0] neg_hi:[1,0,0]
	v_pk_fma_f32 v[242:243], v[206:207], v[14:15], v[242:243] neg_lo:[1,0,0] neg_hi:[1,0,0]
	v_pk_fma_f32 v[242:243], v[208:209], v[16:17], v[242:243] neg_lo:[1,0,0] neg_hi:[1,0,0]
	v_pk_fma_f32 v[242:243], v[210:211], v[18:19], v[242:243] neg_lo:[1,0,0] neg_hi:[1,0,0]
	v_pk_fma_f32 v[242:243], v[212:213], v[20:21], v[242:243] neg_lo:[1,0,0] neg_hi:[1,0,0]
	v_pk_fma_f32 v[242:243], v[214:215], v[22:23], v[242:243] neg_lo:[1,0,0] neg_hi:[1,0,0]
	v_pk_fma_f32 v[242:243], v[216:217], v[24:25], v[242:243] neg_lo:[1,0,0] neg_hi:[1,0,0]
	v_pk_fma_f32 v[242:243], v[218:219], v[26:27], v[242:243] neg_lo:[1,0,0] neg_hi:[1,0,0]
	v_pk_fma_f32 v[242:243], v[220:221], v[28:29], v[242:243] neg_lo:[1,0,0] neg_hi:[1,0,0]
	v_pk_fma_f32 v[242:243], v[222:223], v[30:31], v[242:243] neg_lo:[1,0,0] neg_hi:[1,0,0]
	v_cndmask_b32_e64 v240, 0, 1.0, vcc
	v_fma_f32 v242, -v224, v32, v242
	v_add_f32_e32 v33, v242, v243
	v_cmp_eq_u32_e32 vcc, 23, v95
	ds_read_b128 v[204:207], v11 offset:5888
	ds_read_b128 v[208:211], v11 offset:5904
	ds_read_b128 v[212:215], v11 offset:5920
	ds_read_b128 v[216:219], v11 offset:5936
	ds_read_b128 v[220:223], v11 offset:5952
	ds_read_b128 v[224:227], v11 offset:5968
	s_waitcnt lgkmcnt(6)
	v_pk_fma_f32 v[242:243], v[172:173], v[12:13], v[240:241] neg_lo:[1,0,0] neg_hi:[1,0,0]
	v_pk_fma_f32 v[242:243], v[174:175], v[14:15], v[242:243] neg_lo:[1,0,0] neg_hi:[1,0,0]
	v_pk_fma_f32 v[242:243], v[176:177], v[16:17], v[242:243] neg_lo:[1,0,0] neg_hi:[1,0,0]
	v_pk_fma_f32 v[242:243], v[178:179], v[18:19], v[242:243] neg_lo:[1,0,0] neg_hi:[1,0,0]
	v_pk_fma_f32 v[242:243], v[180:181], v[20:21], v[242:243] neg_lo:[1,0,0] neg_hi:[1,0,0]
	v_pk_fma_f32 v[242:243], v[182:183], v[22:23], v[242:243] neg_lo:[1,0,0] neg_hi:[1,0,0]
	v_pk_fma_f32 v[242:243], v[184:185], v[24:25], v[242:243] neg_lo:[1,0,0] neg_hi:[1,0,0]
	v_pk_fma_f32 v[242:243], v[186:187], v[26:27], v[242:243] neg_lo:[1,0,0] neg_hi:[1,0,0]
	v_pk_fma_f32 v[242:243], v[188:189], v[28:29], v[242:243] neg_lo:[1,0,0] neg_hi:[1,0,0]
	v_pk_fma_f32 v[242:243], v[190:191], v[30:31], v[242:243] neg_lo:[1,0,0] neg_hi:[1,0,0]
	v_pk_fma_f32 v[242:243], v[192:193], v[32:33], v[242:243] neg_lo:[1,0,0] neg_hi:[1,0,0]
	v_cndmask_b32_e64 v248, 0, 1.0, vcc
	v_add_f32_e32 v34, v242, v243
	v_cmp_eq_u32_e32 vcc, 24, v95
	ds_read_b128 v[172:175], v11 offset:6144
	ds_read_b128 v[176:179], v11 offset:6160
	ds_read_b128 v[180:183], v11 offset:6176
	ds_read_b128 v[184:187], v11 offset:6192
	ds_read_b128 v[188:191], v11 offset:6208
	ds_read_b128 v[192:195], v11 offset:6224
	s_waitcnt lgkmcnt(6)
	v_pk_fma_f32 v[242:243], v[204:205], v[12:13], v[248:249] neg_lo:[1,0,0] neg_hi:[1,0,0]
	v_pk_fma_f32 v[242:243], v[206:207], v[14:15], v[242:243] neg_lo:[1,0,0] neg_hi:[1,0,0]
	v_pk_fma_f32 v[242:243], v[208:209], v[16:17], v[242:243] neg_lo:[1,0,0] neg_hi:[1,0,0]
	v_pk_fma_f32 v[242:243], v[210:211], v[18:19], v[242:243] neg_lo:[1,0,0] neg_hi:[1,0,0]
	v_pk_fma_f32 v[242:243], v[212:213], v[20:21], v[242:243] neg_lo:[1,0,0] neg_hi:[1,0,0]
	v_pk_fma_f32 v[242:243], v[214:215], v[22:23], v[242:243] neg_lo:[1,0,0] neg_hi:[1,0,0]
	v_pk_fma_f32 v[242:243], v[216:217], v[24:25], v[242:243] neg_lo:[1,0,0] neg_hi:[1,0,0]
	v_pk_fma_f32 v[242:243], v[218:219], v[26:27], v[242:243] neg_lo:[1,0,0] neg_hi:[1,0,0]
	v_pk_fma_f32 v[242:243], v[220:221], v[28:29], v[242:243] neg_lo:[1,0,0] neg_hi:[1,0,0]
	v_pk_fma_f32 v[242:243], v[222:223], v[30:31], v[242:243] neg_lo:[1,0,0] neg_hi:[1,0,0]
	v_pk_fma_f32 v[242:243], v[224:225], v[32:33], v[242:243] neg_lo:[1,0,0] neg_hi:[1,0,0]
	v_cndmask_b32_e64 v240, 0, 1.0, vcc
	v_fma_f32 v242, -v226, v34, v242
	v_add_f32_e32 v35, v242, v243
	v_cmp_eq_u32_e32 vcc, 25, v95
	ds_read_b128 v[204:207], v11 offset:6400
	ds_read_b128 v[208:211], v11 offset:6416
	ds_read_b128 v[212:215], v11 offset:6432
	ds_read_b128 v[216:219], v11 offset:6448
	ds_read_b128 v[220:223], v11 offset:6464
	ds_read_b128 v[224:227], v11 offset:6480
	ds_read_b128 v[232:235], v11 offset:6496
	s_waitcnt lgkmcnt(7)
	v_pk_fma_f32 v[242:243], v[172:173], v[12:13], v[240:241] neg_lo:[1,0,0] neg_hi:[1,0,0]
	v_pk_fma_f32 v[242:243], v[174:175], v[14:15], v[242:243] neg_lo:[1,0,0] neg_hi:[1,0,0]
	v_pk_fma_f32 v[242:243], v[176:177], v[16:17], v[242:243] neg_lo:[1,0,0] neg_hi:[1,0,0]
	v_pk_fma_f32 v[242:243], v[178:179], v[18:19], v[242:243] neg_lo:[1,0,0] neg_hi:[1,0,0]
	v_pk_fma_f32 v[242:243], v[180:181], v[20:21], v[242:243] neg_lo:[1,0,0] neg_hi:[1,0,0]
	v_pk_fma_f32 v[242:243], v[182:183], v[22:23], v[242:243] neg_lo:[1,0,0] neg_hi:[1,0,0]
	v_pk_fma_f32 v[242:243], v[184:185], v[24:25], v[242:243] neg_lo:[1,0,0] neg_hi:[1,0,0]
	v_pk_fma_f32 v[242:243], v[186:187], v[26:27], v[242:243] neg_lo:[1,0,0] neg_hi:[1,0,0]
	v_pk_fma_f32 v[242:243], v[188:189], v[28:29], v[242:243] neg_lo:[1,0,0] neg_hi:[1,0,0]
	v_pk_fma_f32 v[242:243], v[190:191], v[30:31], v[242:243] neg_lo:[1,0,0] neg_hi:[1,0,0]
	v_pk_fma_f32 v[242:243], v[192:193], v[32:33], v[242:243] neg_lo:[1,0,0] neg_hi:[1,0,0]
	v_pk_fma_f32 v[242:243], v[194:195], v[34:35], v[242:243] neg_lo:[1,0,0] neg_hi:[1,0,0]
	v_cndmask_b32_e64 v248, 0, 1.0, vcc
	v_add_f32_e32 v36, v242, v243
	v_cmp_eq_u32_e32 vcc, 26, v95
	ds_read_b128 v[172:175], v11 offset:6656
	ds_read_b128 v[176:179], v11 offset:6672
	ds_read_b128 v[180:183], v11 offset:6688
	ds_read_b128 v[184:187], v11 offset:6704
	ds_read_b128 v[188:191], v11 offset:6720
	ds_read_b128 v[192:195], v11 offset:6736
	ds_read_b128 v[196:199], v11 offset:6752
	s_waitcnt lgkmcnt(7)
	v_pk_fma_f32 v[242:243], v[204:205], v[12:13], v[248:249] neg_lo:[1,0,0] neg_hi:[1,0,0]
	v_pk_fma_f32 v[242:243], v[206:207], v[14:15], v[242:243] neg_lo:[1,0,0] neg_hi:[1,0,0]
	v_pk_fma_f32 v[242:243], v[208:209], v[16:17], v[242:243] neg_lo:[1,0,0] neg_hi:[1,0,0]
	v_pk_fma_f32 v[242:243], v[210:211], v[18:19], v[242:243] neg_lo:[1,0,0] neg_hi:[1,0,0]
	v_pk_fma_f32 v[242:243], v[212:213], v[20:21], v[242:243] neg_lo:[1,0,0] neg_hi:[1,0,0]
	v_pk_fma_f32 v[242:243], v[214:215], v[22:23], v[242:243] neg_lo:[1,0,0] neg_hi:[1,0,0]
	v_pk_fma_f32 v[242:243], v[216:217], v[24:25], v[242:243] neg_lo:[1,0,0] neg_hi:[1,0,0]
	v_pk_fma_f32 v[242:243], v[218:219], v[26:27], v[242:243] neg_lo:[1,0,0] neg_hi:[1,0,0]
	v_pk_fma_f32 v[242:243], v[220:221], v[28:29], v[242:243] neg_lo:[1,0,0] neg_hi:[1,0,0]
	v_pk_fma_f32 v[242:243], v[222:223], v[30:31], v[242:243] neg_lo:[1,0,0] neg_hi:[1,0,0]
	v_pk_fma_f32 v[242:243], v[224:225], v[32:33], v[242:243] neg_lo:[1,0,0] neg_hi:[1,0,0]
	v_pk_fma_f32 v[242:243], v[226:227], v[34:35], v[242:243] neg_lo:[1,0,0] neg_hi:[1,0,0]
	v_cndmask_b32_e64 v240, 0, 1.0, vcc
	v_fma_f32 v242, -v232, v36, v242
	v_add_f32_e32 v37, v242, v243
	v_cmp_eq_u32_e32 vcc, 27, v95
	ds_read_b128 v[204:207], v11 offset:6912
	ds_read_b128 v[208:211], v11 offset:6928
	ds_read_b128 v[212:215], v11 offset:6944
	ds_read_b128 v[216:219], v11 offset:6960
	ds_read_b128 v[220:223], v11 offset:6976
	ds_read_b128 v[224:227], v11 offset:6992
	ds_read_b128 v[232:235], v11 offset:7008
	s_waitcnt lgkmcnt(7)
	v_pk_fma_f32 v[242:243], v[172:173], v[12:13], v[240:241] neg_lo:[1,0,0] neg_hi:[1,0,0]
	v_pk_fma_f32 v[242:243], v[174:175], v[14:15], v[242:243] neg_lo:[1,0,0] neg_hi:[1,0,0]
	v_pk_fma_f32 v[242:243], v[176:177], v[16:17], v[242:243] neg_lo:[1,0,0] neg_hi:[1,0,0]
	v_pk_fma_f32 v[242:243], v[178:179], v[18:19], v[242:243] neg_lo:[1,0,0] neg_hi:[1,0,0]
	v_pk_fma_f32 v[242:243], v[180:181], v[20:21], v[242:243] neg_lo:[1,0,0] neg_hi:[1,0,0]
	v_pk_fma_f32 v[242:243], v[182:183], v[22:23], v[242:243] neg_lo:[1,0,0] neg_hi:[1,0,0]
	v_pk_fma_f32 v[242:243], v[184:185], v[24:25], v[242:243] neg_lo:[1,0,0] neg_hi:[1,0,0]
	v_pk_fma_f32 v[242:243], v[186:187], v[26:27], v[242:243] neg_lo:[1,0,0] neg_hi:[1,0,0]
	v_pk_fma_f32 v[242:243], v[188:189], v[28:29], v[242:243] neg_lo:[1,0,0] neg_hi:[1,0,0]
	v_pk_fma_f32 v[242:243], v[190:191], v[30:31], v[242:243] neg_lo:[1,0,0] neg_hi:[1,0,0]
	v_pk_fma_f32 v[242:243], v[192:193], v[32:33], v[242:243] neg_lo:[1,0,0] neg_hi:[1,0,0]
	v_pk_fma_f32 v[242:243], v[194:195], v[34:35], v[242:243] neg_lo:[1,0,0] neg_hi:[1,0,0]
	v_pk_fma_f32 v[242:243], v[196:197], v[36:37], v[242:243] neg_lo:[1,0,0] neg_hi:[1,0,0]
	v_cndmask_b32_e64 v248, 0, 1.0, vcc
	v_add_f32_e32 v38, v242, v243
	v_cmp_eq_u32_e32 vcc, 28, v95
	ds_read_b128 v[172:175], v11 offset:7168
	ds_read_b128 v[176:179], v11 offset:7184
	ds_read_b128 v[180:183], v11 offset:7200
	ds_read_b128 v[184:187], v11 offset:7216
	ds_read_b128 v[188:191], v11 offset:7232
	ds_read_b128 v[192:195], v11 offset:7248
	ds_read_b128 v[196:199], v11 offset:7264
	s_waitcnt lgkmcnt(7)
	v_pk_fma_f32 v[242:243], v[204:205], v[12:13], v[248:249] neg_lo:[1,0,0] neg_hi:[1,0,0]
	v_pk_fma_f32 v[242:243], v[206:207], v[14:15], v[242:243] neg_lo:[1,0,0] neg_hi:[1,0,0]
	v_pk_fma_f32 v[242:243], v[208:209], v[16:17], v[242:243] neg_lo:[1,0,0] neg_hi:[1,0,0]
	v_pk_fma_f32 v[242:243], v[210:211], v[18:19], v[242:243] neg_lo:[1,0,0] neg_hi:[1,0,0]
	v_pk_fma_f32 v[242:243], v[212:213], v[20:21], v[242:243] neg_lo:[1,0,0] neg_hi:[1,0,0]
	v_pk_fma_f32 v[242:243], v[214:215], v[22:23], v[242:243] neg_lo:[1,0,0] neg_hi:[1,0,0]
	v_pk_fma_f32 v[242:243], v[216:217], v[24:25], v[242:243] neg_lo:[1,0,0] neg_hi:[1,0,0]
	v_pk_fma_f32 v[242:243], v[218:219], v[26:27], v[242:243] neg_lo:[1,0,0] neg_hi:[1,0,0]
	v_pk_fma_f32 v[242:243], v[220:221], v[28:29], v[242:243] neg_lo:[1,0,0] neg_hi:[1,0,0]
	v_pk_fma_f32 v[242:243], v[222:223], v[30:31], v[242:243] neg_lo:[1,0,0] neg_hi:[1,0,0]
	v_pk_fma_f32 v[242:243], v[224:225], v[32:33], v[242:243] neg_lo:[1,0,0] neg_hi:[1,0,0]
	v_pk_fma_f32 v[242:243], v[226:227], v[34:35], v[242:243] neg_lo:[1,0,0] neg_hi:[1,0,0]
	v_pk_fma_f32 v[242:243], v[232:233], v[36:37], v[242:243] neg_lo:[1,0,0] neg_hi:[1,0,0]
	v_cndmask_b32_e64 v240, 0, 1.0, vcc
	v_fma_f32 v242, -v234, v38, v242
	v_add_f32_e32 v39, v242, v243
	v_cmp_eq_u32_e32 vcc, 29, v95
	ds_read_b128 v[204:207], v11 offset:7424
	ds_read_b128 v[208:211], v11 offset:7440
	ds_read_b128 v[212:215], v11 offset:7456
	ds_read_b128 v[216:219], v11 offset:7472
	ds_read_b128 v[220:223], v11 offset:7488
	ds_read_b128 v[224:227], v11 offset:7504
	ds_read_b128 v[232:235], v11 offset:7520
	ds_read_b128 v[236:239], v11 offset:7536
	s_waitcnt lgkmcnt(8)
	v_pk_fma_f32 v[242:243], v[172:173], v[12:13], v[240:241] neg_lo:[1,0,0] neg_hi:[1,0,0]
	v_pk_fma_f32 v[242:243], v[174:175], v[14:15], v[242:243] neg_lo:[1,0,0] neg_hi:[1,0,0]
	v_pk_fma_f32 v[242:243], v[176:177], v[16:17], v[242:243] neg_lo:[1,0,0] neg_hi:[1,0,0]
	v_pk_fma_f32 v[242:243], v[178:179], v[18:19], v[242:243] neg_lo:[1,0,0] neg_hi:[1,0,0]
	v_pk_fma_f32 v[242:243], v[180:181], v[20:21], v[242:243] neg_lo:[1,0,0] neg_hi:[1,0,0]
	v_pk_fma_f32 v[242:243], v[182:183], v[22:23], v[242:243] neg_lo:[1,0,0] neg_hi:[1,0,0]
	v_pk_fma_f32 v[242:243], v[184:185], v[24:25], v[242:243] neg_lo:[1,0,0] neg_hi:[1,0,0]
	v_pk_fma_f32 v[242:243], v[186:187], v[26:27], v[242:243] neg_lo:[1,0,0] neg_hi:[1,0,0]
	v_pk_fma_f32 v[242:243], v[188:189], v[28:29], v[242:243] neg_lo:[1,0,0] neg_hi:[1,0,0]
	v_pk_fma_f32 v[242:243], v[190:191], v[30:31], v[242:243] neg_lo:[1,0,0] neg_hi:[1,0,0]
	v_pk_fma_f32 v[242:243], v[192:193], v[32:33], v[242:243] neg_lo:[1,0,0] neg_hi:[1,0,0]
	v_pk_fma_f32 v[242:243], v[194:195], v[34:35], v[242:243] neg_lo:[1,0,0] neg_hi:[1,0,0]
	v_pk_fma_f32 v[242:243], v[196:197], v[36:37], v[242:243] neg_lo:[1,0,0] neg_hi:[1,0,0]
	v_pk_fma_f32 v[242:243], v[198:199], v[38:39], v[242:243] neg_lo:[1,0,0] neg_hi:[1,0,0]
	v_cndmask_b32_e64 v248, 0, 1.0, vcc
	v_add_f32_e32 v40, v242, v243
	v_cmp_eq_u32_e32 vcc, 30, v95
	ds_read_b128 v[172:175], v11 offset:7680
	ds_read_b128 v[176:179], v11 offset:7696
	ds_read_b128 v[180:183], v11 offset:7712
	ds_read_b128 v[184:187], v11 offset:7728
	ds_read_b128 v[188:191], v11 offset:7744
	ds_read_b128 v[192:195], v11 offset:7760
	ds_read_b128 v[196:199], v11 offset:7776
	ds_read_b128 v[200:203], v11 offset:7792
	s_waitcnt lgkmcnt(8)
	v_pk_fma_f32 v[242:243], v[204:205], v[12:13], v[248:249] neg_lo:[1,0,0] neg_hi:[1,0,0]
	v_pk_fma_f32 v[242:243], v[206:207], v[14:15], v[242:243] neg_lo:[1,0,0] neg_hi:[1,0,0]
	v_pk_fma_f32 v[242:243], v[208:209], v[16:17], v[242:243] neg_lo:[1,0,0] neg_hi:[1,0,0]
	v_pk_fma_f32 v[242:243], v[210:211], v[18:19], v[242:243] neg_lo:[1,0,0] neg_hi:[1,0,0]
	v_pk_fma_f32 v[242:243], v[212:213], v[20:21], v[242:243] neg_lo:[1,0,0] neg_hi:[1,0,0]
	v_pk_fma_f32 v[242:243], v[214:215], v[22:23], v[242:243] neg_lo:[1,0,0] neg_hi:[1,0,0]
	v_pk_fma_f32 v[242:243], v[216:217], v[24:25], v[242:243] neg_lo:[1,0,0] neg_hi:[1,0,0]
	v_pk_fma_f32 v[242:243], v[218:219], v[26:27], v[242:243] neg_lo:[1,0,0] neg_hi:[1,0,0]
	v_pk_fma_f32 v[242:243], v[220:221], v[28:29], v[242:243] neg_lo:[1,0,0] neg_hi:[1,0,0]
	v_pk_fma_f32 v[242:243], v[222:223], v[30:31], v[242:243] neg_lo:[1,0,0] neg_hi:[1,0,0]
	v_pk_fma_f32 v[242:243], v[224:225], v[32:33], v[242:243] neg_lo:[1,0,0] neg_hi:[1,0,0]
	v_pk_fma_f32 v[242:243], v[226:227], v[34:35], v[242:243] neg_lo:[1,0,0] neg_hi:[1,0,0]
	v_pk_fma_f32 v[242:243], v[232:233], v[36:37], v[242:243] neg_lo:[1,0,0] neg_hi:[1,0,0]
	v_pk_fma_f32 v[242:243], v[234:235], v[38:39], v[242:243] neg_lo:[1,0,0] neg_hi:[1,0,0]
	v_cndmask_b32_e64 v240, 0, 1.0, vcc
	v_fma_f32 v242, -v236, v40, v242
	v_add_f32_e32 v41, v242, v243
	v_cmp_eq_u32_e32 vcc, 31, v95
	ds_read_b128 v[204:207], v11 offset:7936
	ds_read_b128 v[208:211], v11 offset:7952
	ds_read_b128 v[212:215], v11 offset:7968
	ds_read_b128 v[216:219], v11 offset:7984
	ds_read_b128 v[220:223], v11 offset:8000
	ds_read_b128 v[224:227], v11 offset:8016
	ds_read_b128 v[232:235], v11 offset:8032
	ds_read_b128 v[236:239], v11 offset:8048
	s_waitcnt lgkmcnt(8)
	v_pk_fma_f32 v[242:243], v[172:173], v[12:13], v[240:241] neg_lo:[1,0,0] neg_hi:[1,0,0]
	v_pk_fma_f32 v[242:243], v[174:175], v[14:15], v[242:243] neg_lo:[1,0,0] neg_hi:[1,0,0]
	v_pk_fma_f32 v[242:243], v[176:177], v[16:17], v[242:243] neg_lo:[1,0,0] neg_hi:[1,0,0]
	v_pk_fma_f32 v[242:243], v[178:179], v[18:19], v[242:243] neg_lo:[1,0,0] neg_hi:[1,0,0]
	v_pk_fma_f32 v[242:243], v[180:181], v[20:21], v[242:243] neg_lo:[1,0,0] neg_hi:[1,0,0]
	v_pk_fma_f32 v[242:243], v[182:183], v[22:23], v[242:243] neg_lo:[1,0,0] neg_hi:[1,0,0]
	v_pk_fma_f32 v[242:243], v[184:185], v[24:25], v[242:243] neg_lo:[1,0,0] neg_hi:[1,0,0]
	v_pk_fma_f32 v[242:243], v[186:187], v[26:27], v[242:243] neg_lo:[1,0,0] neg_hi:[1,0,0]
	v_pk_fma_f32 v[242:243], v[188:189], v[28:29], v[242:243] neg_lo:[1,0,0] neg_hi:[1,0,0]
	v_pk_fma_f32 v[242:243], v[190:191], v[30:31], v[242:243] neg_lo:[1,0,0] neg_hi:[1,0,0]
	v_pk_fma_f32 v[242:243], v[192:193], v[32:33], v[242:243] neg_lo:[1,0,0] neg_hi:[1,0,0]
	v_pk_fma_f32 v[242:243], v[194:195], v[34:35], v[242:243] neg_lo:[1,0,0] neg_hi:[1,0,0]
	v_pk_fma_f32 v[242:243], v[196:197], v[36:37], v[242:243] neg_lo:[1,0,0] neg_hi:[1,0,0]
	v_pk_fma_f32 v[242:243], v[198:199], v[38:39], v[242:243] neg_lo:[1,0,0] neg_hi:[1,0,0]
	v_pk_fma_f32 v[242:243], v[200:201], v[40:41], v[242:243] neg_lo:[1,0,0] neg_hi:[1,0,0]
	v_cndmask_b32_e64 v248, 0, 1.0, vcc
	v_add_f32_e32 v42, v242, v243
	s_waitcnt lgkmcnt(0)
	v_pk_fma_f32 v[242:243], v[204:205], v[12:13], v[248:249] neg_lo:[1,0,0] neg_hi:[1,0,0]
	v_pk_fma_f32 v[242:243], v[206:207], v[14:15], v[242:243] neg_lo:[1,0,0] neg_hi:[1,0,0]
	v_pk_fma_f32 v[242:243], v[208:209], v[16:17], v[242:243] neg_lo:[1,0,0] neg_hi:[1,0,0]
	v_pk_fma_f32 v[242:243], v[210:211], v[18:19], v[242:243] neg_lo:[1,0,0] neg_hi:[1,0,0]
	v_pk_fma_f32 v[242:243], v[212:213], v[20:21], v[242:243] neg_lo:[1,0,0] neg_hi:[1,0,0]
	v_pk_fma_f32 v[242:243], v[214:215], v[22:23], v[242:243] neg_lo:[1,0,0] neg_hi:[1,0,0]
	v_pk_fma_f32 v[242:243], v[216:217], v[24:25], v[242:243] neg_lo:[1,0,0] neg_hi:[1,0,0]
	v_pk_fma_f32 v[242:243], v[218:219], v[26:27], v[242:243] neg_lo:[1,0,0] neg_hi:[1,0,0]
	v_pk_fma_f32 v[242:243], v[220:221], v[28:29], v[242:243] neg_lo:[1,0,0] neg_hi:[1,0,0]
	v_pk_fma_f32 v[242:243], v[222:223], v[30:31], v[242:243] neg_lo:[1,0,0] neg_hi:[1,0,0]
	v_pk_fma_f32 v[242:243], v[224:225], v[32:33], v[242:243] neg_lo:[1,0,0] neg_hi:[1,0,0]
	v_pk_fma_f32 v[242:243], v[226:227], v[34:35], v[242:243] neg_lo:[1,0,0] neg_hi:[1,0,0]
	v_pk_fma_f32 v[242:243], v[232:233], v[36:37], v[242:243] neg_lo:[1,0,0] neg_hi:[1,0,0]
	v_pk_fma_f32 v[242:243], v[234:235], v[38:39], v[242:243] neg_lo:[1,0,0] neg_hi:[1,0,0]
	v_pk_fma_f32 v[242:243], v[236:237], v[40:41], v[242:243] neg_lo:[1,0,0] neg_hi:[1,0,0]
	v_fma_f32 v242, -v238, v42, v242
	v_add_f32_e32 v43, v242, v243
	v_cvt_pk_bf16_f32 v244, v12, v12
	ds_write_b16 v0, v244
	v_cvt_pk_bf16_f32 v245, v13, v13
	ds_write_b16 v0, v245 offset:80
	v_cvt_pk_bf16_f32 v244, v14, v14
	ds_write_b16 v0, v244 offset:160
	v_cvt_pk_bf16_f32 v245, v15, v15
	ds_write_b16 v0, v245 offset:240
	v_cvt_pk_bf16_f32 v244, v16, v16
	ds_write_b16 v0, v244 offset:320
	v_cvt_pk_bf16_f32 v245, v17, v17
	ds_write_b16 v0, v245 offset:400
	v_cvt_pk_bf16_f32 v244, v18, v18
	ds_write_b16 v0, v244 offset:480
	v_cvt_pk_bf16_f32 v245, v19, v19
	ds_write_b16 v0, v245 offset:560
	v_cvt_pk_bf16_f32 v244, v20, v20
	ds_write_b16 v0, v244 offset:640
	v_cvt_pk_bf16_f32 v245, v21, v21
	ds_write_b16 v0, v245 offset:720
	v_cvt_pk_bf16_f32 v244, v22, v22
	ds_write_b16 v0, v244 offset:800
	v_cvt_pk_bf16_f32 v245, v23, v23
	ds_write_b16 v0, v245 offset:880
	v_cvt_pk_bf16_f32 v244, v24, v24
	ds_write_b16 v0, v244 offset:960
	v_cvt_pk_bf16_f32 v245, v25, v25
	ds_write_b16 v0, v245 offset:1040
	v_cvt_pk_bf16_f32 v244, v26, v26
	ds_write_b16 v0, v244 offset:1120
	v_cvt_pk_bf16_f32 v245, v27, v27
	ds_write_b16 v0, v245 offset:1200
	v_cvt_pk_bf16_f32 v244, v28, v28
	ds_write_b16 v0, v244 offset:1280
	v_cvt_pk_bf16_f32 v245, v29, v29
	ds_write_b16 v0, v245 offset:1360
	v_cvt_pk_bf16_f32 v244, v30, v30
	ds_write_b16 v0, v244 offset:1440
	v_cvt_pk_bf16_f32 v245, v31, v31
	ds_write_b16 v0, v245 offset:1520
	v_cvt_pk_bf16_f32 v244, v32, v32
	ds_write_b16 v0, v244 offset:1600
	v_cvt_pk_bf16_f32 v245, v33, v33
	ds_write_b16 v0, v245 offset:1680
	v_cvt_pk_bf16_f32 v244, v34, v34
	ds_write_b16 v0, v244 offset:1760
	v_cvt_pk_bf16_f32 v245, v35, v35
	ds_write_b16 v0, v245 offset:1840
	v_cvt_pk_bf16_f32 v244, v36, v36
	ds_write_b16 v0, v244 offset:1920
	v_cvt_pk_bf16_f32 v245, v37, v37
	ds_write_b16 v0, v245 offset:2000
	v_cvt_pk_bf16_f32 v244, v38, v38
	ds_write_b16 v0, v244 offset:2080
	v_cvt_pk_bf16_f32 v245, v39, v39
	ds_write_b16 v0, v245 offset:2160
	v_cvt_pk_bf16_f32 v244, v40, v40
	ds_write_b16 v0, v244 offset:2240
	v_cvt_pk_bf16_f32 v245, v41, v41
	ds_write_b16 v0, v245 offset:2320
	v_cvt_pk_bf16_f32 v244, v42, v42
	ds_write_b16 v0, v244 offset:2400
	v_cvt_pk_bf16_f32 v245, v43, v43
	ds_write_b16 v0, v245 offset:2480

amdhsa.kernels:
  - .agpr_count:     0
    .args:
      - .offset:         0
        .size:           280
        .value_kind:     by_value
      - .offset:         280
        .size:           4
        .value_kind:     by_value
      - .offset:         284
        .size:           4
        .value_kind:     by_value
      - .offset:         288
        .size:           4
        .value_kind:     hidden_block_count_x
      - .offset:         292
        .size:           4
        .value_kind:     hidden_block_count_y
      - .offset:         296
        .size:           4
        .value_kind:     hidden_block_count_z
      - .offset:         300
        .size:           2
        .value_kind:     hidden_group_size_x
      - .offset:         302
        .size:           2
        .value_kind:     hidden_group_size_y
      - .offset:         304
        .size:           2
        .value_kind:     hidden_group_size_z
      - .offset:         306
        .size:           2
        .value_kind:     hidden_remainder_x
      - .offset:         308
        .size:           2
        .value_kind:     hidden_remainder_y
      - .offset:         310
        .size:           2
        .value_kind:     hidden_remainder_z
      - .offset:         328
        .size:           8
        .value_kind:     hidden_global_offset_x
      - .offset:         336
        .size:           8
        .value_kind:     hidden_global_offset_y
      - .offset:         344
        .size:           8
        .value_kind:     hidden_global_offset_z
      - .offset:         352
        .size:           2
        .value_kind:     hidden_grid_dims
      - .offset:         376
        .size:           8
        .value_kind:     hidden_multigrid_sync_arg
      - .offset:         408
        .size:           4
        .value_kind:     hidden_dynamic_lds_size
    .group_segment_fixed_size: 0
    .kernarg_segment_align: 8
    .kernarg_segment_size: 544
    .language:       OpenCL C
    .language_version:
      - 2
      - 0
    .max_flat_workgroup_size: 512
    .name:           _Z4mega6Paramsii
    .private_segment_fixed_size: 0
    .sgpr_count:     108
    .sgpr_spill_count: 8
    .symbol:         _Z4mega6Paramsii.kd
    .uniform_work_group_size: 1
    .uses_dynamic_stack: false
    .vgpr_count:     256
    .vgpr_spill_count: 0
    .wavefront_size: 64
